# v62 + in-loop barrier instances: last XCD leader no longer bumps the (now unread) TOPGEN word before its acquire
# speedup vs baseline: 1.0095x; 1.0029x over previous
; __device__ __forceinline__ unsigned xb_ld(unsigned* p)              { return __hip_atomic_load(p, __ATOMIC_RELAXED, __HIP_MEMORY_SCOPE_AGENT); }
; __device__ __forceinline__ unsigned xb_add(unsigned* p, unsigned v) { return __hip_atomic_fetch_add(p, v, __ATOMIC_RELAXED, __HIP_MEMORY_SCOPE_AGENT); }
; #define XB_SPIN(cond, bar) do { unsigned _sp = 0; while (cond) { __builtin_amdgcn_s_sleep(1); \
;     if ((++_sp & 255u) == 0u) { if (xb_ld(&(bar)[XB_TMO])) break; if (_sp > XB_SPIN_CAP) { atomicAdd(&(bar)[XB_TMO], 1u); break; } } } } while (0)
; __device__ __forceinline__ void xcd_barrier(const XcdBarrier& b) {
;     ...
;         const unsigned old = xb_add(&bar[XB_XSUB(b.x)], 1u);
;         const unsigned gen = old / nloc;
;         if (old + 1u == (gen + 1u) * nloc) {
;             __builtin_amdgcn_fence(__ATOMIC_RELEASE, "agent");
;             asm volatile("s_waitcnt vmcnt(0)" ::: "memory");
;             const unsigned og = xb_add(&bar[XB_TOP], 1u);
;             const unsigned tg = og / nx;
;             if (og + 1u == (tg + 1u) * nx) xb_add(&bar[XB_TOPGEN], 1u);
;             else XB_SPIN(xb_ld(&bar[XB_TOPGEN]) == tg, bar);
;             __builtin_amdgcn_fence(__ATOMIC_ACQUIRE, "agent");
;             xb_add(&bar[XB_XGEN(b.x)], 1u);
;             asm volatile("s_waitcnt vmcnt(0)" ::: "memory");
.LBB0_593:
	s_or_b64 exec, exec, s[12:13]
	s_waitcnt vmcnt(0)
	v_readfirstlane_b32 s5, v3
	v_sub_u32_e32 v4, 0, v2
	v_readlane_b32 s10, v254, 17
	v_add_u32_e32 v3, s5, v1
	v_cvt_f32_u32_e32 v1, v2
	v_readlane_b32 s11, v254, 18
	s_mov_b64 s[12:13], 0
	v_rcp_iflag_f32_e32 v1, v1
	s_nop 0
	v_mul_f32_e32 v1, 0x4f7ffffe, v1
	v_cvt_u32_f32_e32 v1, v1
	v_mul_lo_u32 v4, v4, v1
	v_mul_hi_u32 v4, v1, v4
	v_add_u32_e32 v1, v1, v4
	v_mul_hi_u32 v1, v3, v1
	v_mul_lo_u32 v4, v1, v2
	v_sub_u32_e32 v4, v3, v4
	v_cmp_ge_u32_e32 vcc, v4, v2
	v_add_u32_e32 v5, 1, v1
	v_add_u32_e32 v3, 1, v3
	v_cndmask_b32_e32 v1, v1, v5, vcc
	v_sub_u32_e32 v5, v4, v2
	v_cndmask_b32_e32 v4, v4, v5, vcc
	v_cmp_ge_u32_e32 vcc, v4, v2
	v_add_u32_e32 v4, 1, v1
	s_nop 0
	v_cndmask_b32_e32 v1, v1, v4, vcc
	v_mul_lo_u32 v4, v2, v1
	v_add_u32_e32 v2, v4, v2
	v_cmp_ne_u32_e32 vcc, v3, v2
	v_mov_b32_e32 v6, v2
	v_mov_b64_e32 v[2:3], s[10:11]
	s_and_saveexec_b64 s[10:11], vcc
	s_cbranch_execz .LBB0_605
	v_readlane_b32 s12, v254, 15
	v_readlane_b32 s13, v254, 16
	s_mov_b64 s[18:19], 0
	s_nop 3
	global_load_dword v2, v203, s[12:13] sc1
	s_waitcnt vmcnt(0)
	v_cmp_lt_u32_e32 vcc, v2, v6
	s_and_saveexec_b64 s[12:13], vcc
	s_cbranch_execz .LBB0_604
	s_mov_b32 s5, 1
	s_branch .LBB0_597

; __device__ __forceinline__ unsigned xb_ld(unsigned* p)              { return __hip_atomic_load(p, __ATOMIC_RELAXED, __HIP_MEMORY_SCOPE_AGENT); }
; __device__ __forceinline__ unsigned xb_add(unsigned* p, unsigned v) { return __hip_atomic_fetch_add(p, v, __ATOMIC_RELAXED, __HIP_MEMORY_SCOPE_AGENT); }
; #define XB_SPIN(cond, bar) do { unsigned _sp = 0; while (cond) { __builtin_amdgcn_s_sleep(1); \
;     if ((++_sp & 255u) == 0u) { if (xb_ld(&(bar)[XB_TMO])) break; if (_sp > XB_SPIN_CAP) { atomicAdd(&(bar)[XB_TMO], 1u); break; } } } } while (0)
; __device__ __forceinline__ void xcd_barrier(const XcdBarrier& b) {
;     ...
;         const unsigned old = xb_add(&bar[XB_XSUB(b.x)], 1u);
;         const unsigned gen = old / nloc;
;         if (old + 1u == (gen + 1u) * nloc) {
;             __builtin_amdgcn_fence(__ATOMIC_RELEASE, "agent");
;             asm volatile("s_waitcnt vmcnt(0)" ::: "memory");
;             const unsigned og = xb_add(&bar[XB_TOP], 1u);
;             const unsigned tg = og / nx;
;             if (og + 1u == (tg + 1u) * nx) xb_add(&bar[XB_TOPGEN], 1u);
;             else XB_SPIN(xb_ld(&bar[XB_TOPGEN]) == tg, bar);
;             __builtin_amdgcn_fence(__ATOMIC_ACQUIRE, "agent");
;             xb_add(&bar[XB_XGEN(b.x)], 1u);
;             asm volatile("s_waitcnt vmcnt(0)" ::: "memory");
.LBB0_1963:
	s_or_b64 exec, exec, s[10:11]
	s_waitcnt vmcnt(0)
	v_readfirstlane_b32 s4, v3
	v_sub_u32_e32 v4, 0, v2
	s_mov_b64 s[10:11], 0
	v_add_u32_e32 v3, s4, v1
	v_cvt_f32_u32_e32 v1, v2
	v_readlane_b32 s4, v254, 17
	v_readlane_b32 s5, v254, 18
	v_rcp_iflag_f32_e32 v1, v1
	s_nop 0
	v_mul_f32_e32 v1, 0x4f7ffffe, v1
	v_cvt_u32_f32_e32 v1, v1
	v_mul_lo_u32 v4, v4, v1
	v_mul_hi_u32 v4, v1, v4
	v_add_u32_e32 v1, v1, v4
	v_mul_hi_u32 v1, v3, v1
	v_mul_lo_u32 v4, v1, v2
	v_sub_u32_e32 v4, v3, v4
	v_cmp_ge_u32_e32 vcc, v4, v2
	v_add_u32_e32 v5, 1, v1
	v_add_u32_e32 v3, 1, v3
	v_cndmask_b32_e32 v1, v1, v5, vcc
	v_sub_u32_e32 v5, v4, v2
	v_cndmask_b32_e32 v4, v4, v5, vcc
	v_cmp_ge_u32_e32 vcc, v4, v2
	v_add_u32_e32 v4, 1, v1
	s_nop 0
	v_cndmask_b32_e32 v1, v1, v4, vcc
	v_mul_lo_u32 v4, v2, v1
	v_add_u32_e32 v2, v4, v2
	v_cmp_ne_u32_e32 vcc, v3, v2
	v_mov_b32_e32 v6, v2
	v_mov_b64_e32 v[2:3], s[4:5]
	s_and_saveexec_b64 s[8:9], vcc
	s_cbranch_execz .LBB0_1975
	v_readlane_b32 s4, v254, 15
	v_readlane_b32 s5, v254, 16
	s_mov_b64 s[12:13], 0
	s_nop 3
	global_load_dword v2, v203, s[4:5] sc1
	s_waitcnt vmcnt(0)
	v_cmp_lt_u32_e32 vcc, v2, v6
	s_and_saveexec_b64 s[10:11], vcc
	s_cbranch_execz .LBB0_1974
	s_mov_b32 s4, 1
	s_branch .LBB0_1967
